# combo2 + L1 prefetch of the 4 conv-tap rows at top of each mlA conv iteration
# speedup vs baseline: 1.0044x; 1.0031x over previous
.LBB0_1349:
	v_and_b32_e32 v15, 0xf8, v66
	v_mov_b32_e32 v0, s84
	v_mov_b32_e32 v1, s85
	v_cmp_gt_u32_e64 s[60:61], s28, v15
	v_lshl_add_u32 v18, v15, 2, 0
	v_ashrrev_i32_e32 v68, 5, v67
	v_cndmask_b32_e64 v14, v0, v1, s[60:61]
	ds_read_b128 v[0:3], v18 offset:41472
	ds_read_b128 v[4:7], v18 offset:41488
	s_movk_i32 s3, 0x7f
	v_add_u32_e32 v19, s24, v68
	v_cmp_lt_u32_e32 vcc, s3, v15
	v_add_u32_e32 v14, v14, v15
	v_mad_u32_u24 v90, v68, s93, v14
	v_lshl_add_u32 v90, v90, 1, v64
	global_load_dword v86, v90, s[66:67]
	v_add_u32_e32 v91, 0x3400, v90
	global_load_dword v87, v91, s[66:67]
	v_add_u32_e32 v91, 0x6800, v90
	global_load_dword v88, v91, s[66:67]
	v_add_u32_e32 v91, 0x9c00, v90
	global_load_dword v89, v91, s[66:67]
	v_cmp_lt_i32_e64 s[60:61], 2, v19
	s_and_saveexec_b64 s[4:5], s[60:61]
	s_cbranch_execz .LBB0_1351
	v_mad_u64_u32 v[70:71], s[34:35], v68, s93, v[14:15]
	v_lshl_add_u32 v69, v70, 1, v64
	global_load_dwordx4 v[70:73], v69, s[66:67]
	ds_read_b128 v[74:77], v18 offset:37376
	ds_read_b128 v[78:81], v18 offset:37392
	s_waitcnt vmcnt(0)
	v_lshlrev_b32_e32 v82, 16, v70
	v_and_b32_e32 v83, 0xffff0000, v70
	v_lshlrev_b32_e32 v70, 16, v71
	v_and_b32_e32 v71, 0xffff0000, v71
	s_waitcnt lgkmcnt(1)
	v_pk_fma_f32 v[2:3], v[76:77], v[70:71], v[2:3]
	v_lshlrev_b32_e32 v70, 16, v72
	v_and_b32_e32 v71, 0xffff0000, v72
	s_waitcnt lgkmcnt(0)
	v_pk_fma_f32 v[4:5], v[78:79], v[70:71], v[4:5]
	v_lshlrev_b32_e32 v70, 16, v73
	v_and_b32_e32 v71, 0xffff0000, v73
	v_pk_fma_f32 v[0:1], v[74:75], v[82:83], v[0:1]
	v_pk_fma_f32 v[6:7], v[80:81], v[70:71], v[6:7]
